# grid barrier, XCD-leader tail: the XGEN release atomic is issued before the leader's own buffer_inv and no longer waits for the fire-and-forget TOPGEN atomic's ack (16 sites)
# speedup vs baseline: 1.0095x; 1.0055x over previous
; __device__ __forceinline__ unsigned xb_ld(unsigned* p)              { return __hip_atomic_load(p, __ATOMIC_RELAXED, __HIP_MEMORY_SCOPE_AGENT); }
; __device__ __forceinline__ unsigned xb_add(unsigned* p, unsigned v) { return __hip_atomic_fetch_add(p, v, __ATOMIC_RELAXED, __HIP_MEMORY_SCOPE_AGENT); }
; #define XB_SPIN(cond, bar) do { unsigned _sp = 0; while (cond) { __builtin_amdgcn_s_sleep(1); \
;     if ((++_sp & 255u) == 0u) { if (xb_ld(&(bar)[XB_TMO])) break; if (_sp > XB_SPIN_CAP) { atomicAdd(&(bar)[XB_TMO], 1u); break; } } } } while (0)
; __device__ __forceinline__ void xcd_barrier(const XcdBarrier& b, int tid) {
;     ...
;             __builtin_amdgcn_fence(__ATOMIC_RELEASE, "agent");
;             asm volatile("s_waitcnt vmcnt(0)" ::: "memory");
;             const unsigned og = xb_add(&bar[XB_TOP], 1u);
;             const unsigned tg = og / nx;
;             if (og + 1u == (tg + 1u) * nx) xb_add(&bar[XB_TOPGEN], 1u);
;             else XB_SPIN(xb_ld(&bar[XB_TOPGEN]) == tg, bar);
;             __builtin_amdgcn_fence(__ATOMIC_ACQUIRE, "agent");
;             xb_add(&bar[XB_XGEN(b.x)], 1u);
;             asm volatile("s_waitcnt vmcnt(0)" ::: "memory");
.LBB0_358:
	s_or_b64 exec, exec, s[0:1]
	v_readlane_b32 s0, v250, 63
	v_readlane_b32 s1, v251, 0
	s_nop 4
	global_atomic_add v1, v205, s[0:1]
	buffer_inv sc1
	s_waitcnt vmcnt(0)

; __device__ __forceinline__ unsigned xb_ld(unsigned* p)              { return __hip_atomic_load(p, __ATOMIC_RELAXED, __HIP_MEMORY_SCOPE_AGENT); }
; __device__ __forceinline__ unsigned xb_add(unsigned* p, unsigned v) { return __hip_atomic_fetch_add(p, v, __ATOMIC_RELAXED, __HIP_MEMORY_SCOPE_AGENT); }
; #define XB_SPIN(cond, bar) do { unsigned _sp = 0; while (cond) { __builtin_amdgcn_s_sleep(1); \
;     if ((++_sp & 255u) == 0u) { if (xb_ld(&(bar)[XB_TMO])) break; if (_sp > XB_SPIN_CAP) { atomicAdd(&(bar)[XB_TMO], 1u); break; } } } } while (0)
; __device__ __forceinline__ void xcd_barrier(const XcdBarrier& b, int tid) {
;     ...
;             __builtin_amdgcn_fence(__ATOMIC_RELEASE, "agent");
;             asm volatile("s_waitcnt vmcnt(0)" ::: "memory");
;             const unsigned og = xb_add(&bar[XB_TOP], 1u);
;             const unsigned tg = og / nx;
;             if (og + 1u == (tg + 1u) * nx) xb_add(&bar[XB_TOPGEN], 1u);
;             else XB_SPIN(xb_ld(&bar[XB_TOPGEN]) == tg, bar);
;             __builtin_amdgcn_fence(__ATOMIC_ACQUIRE, "agent");
;             xb_add(&bar[XB_XGEN(b.x)], 1u);
;             asm volatile("s_waitcnt vmcnt(0)" ::: "memory");
.LBB0_559:
	s_or_b64 exec, exec, s[4:5]
	v_readlane_b32 s4, v250, 63
	v_readlane_b32 s5, v251, 0
	s_nop 4
	global_atomic_add v1, v205, s[4:5]
	buffer_inv sc1
	s_waitcnt vmcnt(0)

; __device__ __forceinline__ unsigned xb_ld(unsigned* p)              { return __hip_atomic_load(p, __ATOMIC_RELAXED, __HIP_MEMORY_SCOPE_AGENT); }
; __device__ __forceinline__ unsigned xb_add(unsigned* p, unsigned v) { return __hip_atomic_fetch_add(p, v, __ATOMIC_RELAXED, __HIP_MEMORY_SCOPE_AGENT); }
; #define XB_SPIN(cond, bar) do { unsigned _sp = 0; while (cond) { __builtin_amdgcn_s_sleep(1); \
;     if ((++_sp & 255u) == 0u) { if (xb_ld(&(bar)[XB_TMO])) break; if (_sp > XB_SPIN_CAP) { atomicAdd(&(bar)[XB_TMO], 1u); break; } } } } while (0)
; __device__ __forceinline__ void xcd_barrier(const XcdBarrier& b, int tid) {
;     ...
;             __builtin_amdgcn_fence(__ATOMIC_RELEASE, "agent");
;             asm volatile("s_waitcnt vmcnt(0)" ::: "memory");
;             const unsigned og = xb_add(&bar[XB_TOP], 1u);
;             const unsigned tg = og / nx;
;             if (og + 1u == (tg + 1u) * nx) xb_add(&bar[XB_TOPGEN], 1u);
;             else XB_SPIN(xb_ld(&bar[XB_TOPGEN]) == tg, bar);
;             __builtin_amdgcn_fence(__ATOMIC_ACQUIRE, "agent");
;             xb_add(&bar[XB_XGEN(b.x)], 1u);
;             asm volatile("s_waitcnt vmcnt(0)" ::: "memory");
.LBB0_866:
	s_or_b64 exec, exec, s[16:17]
	v_readlane_b32 s4, v250, 63
	v_readlane_b32 s5, v251, 0
	s_nop 4
	global_atomic_add v1, v205, s[4:5]
	buffer_inv sc1
	s_waitcnt vmcnt(0)
